# perm4 + one designated early-finishing WG per XCD (bx>=248) writes back L2 at arrival for the barriers after P1 and P11
# speedup vs baseline: 1.0031x; 1.0031x over previous
.LBB0_617:
	s_waitcnt vmcnt(0)
	s_waitcnt vmcnt(0)
	s_barrier
	s_mov_b64 s[0:1], exec
	v_readlane_b32 s8, v245, 16
	v_readlane_b32 s9, v245, 17
	v_readlane_b32 s22, v244, 19
	s_and_b64 s[8:9], s[0:1], s[8:9]
	v_readlane_b32 s23, v244, 20
	s_mov_b64 exec, s[8:9]
	s_cbranch_execz .LBB0_669
	s_cmp_lt_u32 s2, 0xf8
	s_cbranch_scc1 .Lwb1_skip0
	buffer_wbl2 sc1
	s_waitcnt vmcnt(0)
.Lwb1_skip0:
	s_add_i32 s8, 0, 0x25fc0
	v_mov_b32_e32 v0, s8
	s_waitcnt vmcnt(0) expcnt(0) lgkmcnt(0)
	ds_read_b32 v2, v0
	s_add_i32 s8, 0, 0x25fc4
	v_mov_b32_e32 v0, s8
	ds_read_b32 v0, v0
	s_waitcnt lgkmcnt(1)
	v_cmp_ne_u32_e32 vcc, 0, v2
	s_cbranch_vccnz .LBB0_633
	s_mov_b32 s20, 1
	v_mov_b32_e32 v16, 0
	s_branch .LBB0_621

.LBB0_1383:
	s_waitcnt vmcnt(0)
	s_waitcnt vmcnt(0)
	s_barrier
	s_mov_b64 s[0:1], exec
	v_readlane_b32 s4, v245, 16
	v_readlane_b32 s5, v245, 17
	s_and_b64 s[4:5], s[0:1], s[4:5]
	s_mov_b64 exec, s[4:5]
	s_cbranch_execz .LBB0_1435
	s_cmp_lt_u32 s2, 0xf8
	s_cbranch_scc1 .Lwb1_skip1
	buffer_wbl2 sc1
	s_waitcnt vmcnt(0)
.Lwb1_skip1:
	s_add_i32 s4, 0, 0x25fc0
	v_mov_b32_e32 v0, s4
	s_waitcnt vmcnt(0) expcnt(0) lgkmcnt(0)
	ds_read_b32 v2, v0
	s_add_i32 s4, 0, 0x25fc4
	v_mov_b32_e32 v0, s4
	ds_read_b32 v0, v0
	s_waitcnt lgkmcnt(1)
	v_cmp_ne_u32_e32 vcc, 0, v2
	s_cbranch_vccnz .LBB0_1399
	s_mov_b32 s10, 1
	v_mov_b32_e32 v16, 0
	s_branch .LBB0_1387
